# on top: round-2 tiles of w_o/down as two 128-row half-units on 64 WGs; conversion on WGs>=64, slices 3400/3700
# speedup vs baseline: 1.0114x; 1.0114x over previous
.LBB0_149:
	s_cmp_gt_i32 s84, 31
	v_readlane_b32 s4, v254, 9
	s_cselect_b64 s[0:1], -1, 0
	v_readlane_b32 s5, v254, 10
	s_or_b64 s[0:1], s[0:1], s[4:5]
	s_and_b64 vcc, exec, s[0:1]
	s_cbranch_vccnz .LBB0_187
	s_cmp_eq_u32 s91, 5
	s_movk_i32 s0, 0xd48
	s_cselect_b32 s20, s0, 0xe74
	s_movk_i32 s0, 0x1080
	v_readfirstlane_b32 s22, v193
	s_cselect_b32 s23, 0xe74, s0
	s_and_b64 s[0:1], s[56:57], exec
	s_cselect_b32 s26, 0, s20
	s_lshr_b32 s22, s22, 8
	s_and_b64 s[0:1], s[56:57], exec
	v_readlane_b32 s0, v254, 12
	s_cselect_b32 s20, 0xd48, s23
	s_add_i32 s0, s0, s26
	s_add_i32 s50, s0, s22
	s_waitcnt vmcnt(0)
	v_mov_b32_e32 v1, v218
	s_cmp_ge_i32 s50, s20
	s_waitcnt vmcnt(0) lgkmcnt(0)
	s_barrier
	s_cbranch_scc1 .LBB0_187
	v_readlane_b32 s0, v254, 0
	v_readlane_b32 s1, v254, 1
	s_load_dword s0, s[0:1], 0x0
	s_add_i32 s28, s92, 1
	v_readlane_b32 s52, v253, 0
	v_readlane_b32 s54, v253, 2
	v_readlane_b32 s55, v253, 3
	s_waitcnt lgkmcnt(0)
	s_lshl_b32 s0, s0, 1
	s_sub_i32 s51, s0, 0x80
	s_bitcmp1_b32 s28, 0
	s_cselect_b32 s0, 0x2180000, 0
	s_add_u32 s38, s54, s0
	v_readlane_b32 s56, v253, 4
	s_addc_u32 s39, s55, 0
	v_readlane_b32 s57, v253, 5
	s_add_u32 s40, s56, s0
	v_readlane_b32 s58, v253, 6
	s_addc_u32 s41, s57, 0
	v_cvt_f32_i32_e32 v7, v1
	v_readlane_b32 s59, v253, 7
	s_add_u32 s42, s58, s0
	v_readlane_b32 s60, v253, 8
	s_addc_u32 s43, s59, 0
	v_readlane_b32 s61, v253, 9
	s_add_u32 s44, s60, s0
	v_readlane_b32 s62, v253, 10
	s_addc_u32 s45, s61, 0
	v_mul_f32_e32 v7, 0x3d000000, v7
	v_readlane_b32 s63, v253, 11
	s_add_u32 s46, s62, s0
	v_readlane_b32 s4, v253, 32
	v_mul_f32_e64 v8, |v7|, 0.5
	s_mul_i32 s22, s28, 0x1900000
	s_addc_u32 s47, s63, 0
	s_ashr_i32 s29, s28, 31
	v_readlane_b32 s18, v253, 46
	v_fract_f32_e32 v9, v8
	s_mul_hi_i32 s1, s28, 0x1900000
	v_readlane_b32 s19, v253, 47
	s_add_u32 s48, s18, s22
	v_add_f32_e32 v9, v9, v9
	v_cmp_neq_f32_e32 vcc, s21, v8
	s_addc_u32 s49, s19, s1
	v_cmp_gt_f32_e64 s[0:1], |v7|, 1.0
	v_cndmask_b32_e32 v8, 0, v9, vcc
	v_readlane_b32 s53, v253, 1
	v_cndmask_b32_e64 v8, |v7|, v8, s[0:1]
	v_add_f32_e32 v9, v8, v8
	v_rndne_f32_e32 v9, v9
	v_fmac_f32_e32 v8, -0.5, v9
	v_mul_f32_e32 v11, v8, v8
	v_fmamk_f32 v12, v11, 0x3e75aa41, v220
	v_fmaak_f32 v12, v11, v12, 0x40234736
	v_fmaak_f32 v12, v11, v12, 0xc0a55e0e
	v_mul_f32_e32 v13, v8, v11
	v_mul_f32_e32 v12, v13, v12
	v_cvt_i32_f32_e32 v10, v9
	v_fmac_f32_e32 v12, 0x40490fdb, v8
	v_fmamk_f32 v8, v11, 0x3d4be544, v221
	v_fmaak_f32 v8, v11, v8, 0xbfaad1da
	v_fmaak_f32 v8, v11, v8, 0x4081e0d3
	v_fmaak_f32 v8, v11, v8, 0xc09de9e6
	v_fma_f32 v8, v11, v8, 1.0
	v_and_b32_e32 v11, 1, v10
	v_readlane_b32 s64, v253, 12
	v_readlane_b32 s65, v253, 13
	v_readlane_b32 s66, v253, 14
	v_readlane_b32 s67, v253, 15
	v_lshlrev_b32_e32 v6, 2, v1
	v_cmp_eq_u32_e32 vcc, 0, v11
	v_readlane_b32 s52, v253, 48
	v_ashrrev_i32_e32 v0, 4, v1
	v_and_b32_e32 v2, 60, v6
	v_and_b32_e32 v34, 63, v1
	v_ashrrev_i32_e32 v35, 2, v1
	v_cmp_gt_i32_e64 s[36:37], 64, v1
	v_and_b32_e32 v1, 0x7fffffff, v7
	v_and_b32_e32 v9, 2, v10
	v_cndmask_b32_e64 v11, -v12, v8, vcc
	v_add_u32_e32 v39, s2, v6
	v_cndmask_b32_e32 v6, v8, v12, vcc
	v_lshlrev_b32_e32 v8, 30, v10
	s_lshl_b64 s[22:23], s[28:29], 22
	v_readlane_b32 s60, v253, 56
	v_cmp_eq_u32_e64 s[0:1], 0, v9
	v_and_b32_e32 v8, 0x80000000, v8
	v_xor_b32_e32 v1, v1, v7
	v_readlane_b32 s53, v253, 49
	v_readlane_b32 s61, v253, 57
	s_add_u32 s52, s60, s22
	v_cndmask_b32_e64 v9, -v11, v11, s[0:1]
	s_movk_i32 s0, 0x1f8
	v_xor_b32_e32 v1, v1, v8
	s_addc_u32 s53, s61, s23
	s_lshl_b64 s[34:35], s[28:29], 16
	s_lshl_b64 s[30:31], s[28:29], 10
	v_cmp_class_f32_e64 s[0:1], v7, s0
	v_xor_b32_e32 v1, v1, v6
	v_readlane_b32 s54, v253, 50
	s_add_u32 s29, s52, 0x300000
	v_and_b32_e32 v3, -16, v35
	v_cndmask_b32_e64 v38, v236, v9, s[0:1]
	v_cndmask_b32_e64 v40, v236, v1, s[0:1]
	s_movk_i32 s0, 0x41
	v_readlane_b32 s56, v253, 52
	s_addc_u32 s54, s53, 0
	v_mad_u64_u32 v[10:11], s[0:1], v0, s0, v[2:3]
	v_readlane_b32 s57, v253, 53
	s_add_u32 s0, s56, s34
	v_readlane_b32 s58, v253, 54
	s_addc_u32 s1, s57, s35
	v_readlane_b32 s55, v253, 51
	v_readlane_b32 s59, v253, 55
	s_add_u32 s26, s58, s30
	v_readlane_b32 s66, v253, 62
	s_mul_i32 s55, s28, 0xb00000
	s_addc_u32 s27, s59, s31
	v_readlane_b32 s67, v253, 63
	s_mul_hi_i32 s33, s28, 0xb00000
	s_mul_hi_i32 s60, s28, 0x1600000
	s_mul_i32 s61, s28, 0x1600000
	s_add_u32 s28, s66, s55
	v_readlane_b32 s64, v253, 60
	s_addc_u32 s30, s67, s33
	v_readlane_b32 s65, v253, 61
	s_add_u32 s31, s64, s61
	v_readlane_b32 s62, v253, 58
	v_lshlrev_b32_e32 v184, 1, v34
	v_mov_b32_e32 v36, s2
	v_ashrrev_i32_e32 v1, 31, v0
	v_add_u32_e32 v12, 16, v0
	s_addc_u32 s34, s65, s60
	v_readlane_b32 s63, v253, 59
	v_lshl_add_u64 v[4:5], s[40:41], 0, v[184:185]
	v_lshl_add_u64 v[6:7], s[38:39], 0, v[184:185]
	v_lshl_add_u32 v41, v10, 2, s2
	v_lshlrev_b64 v[10:11], 12, v[0:1]
	v_ashrrev_i32_e32 v13, 31, v12
	v_add_u32_e32 v18, 32, v0
	v_add_u32_e32 v24, 48, v0
	v_lshlrev_b32_e32 v184, 2, v2
	v_mad_u32_u24 v1, v34, s90, v36
	s_add_u32 s22, s62, s22
	v_lshrrev_b32_e32 v34, 4, v35
	v_lshlrev_b32_e32 v8, 6, v0
	v_lshlrev_b32_e32 v14, 6, v12
	v_lshlrev_b64 v[16:17], 12, v[12:13]
	v_lshlrev_b32_e32 v20, 6, v18
	v_ashrrev_i32_e32 v19, 31, v18
	v_lshlrev_b32_e32 v26, 6, v24
	v_ashrrev_i32_e32 v25, 31, v24
	v_lshl_add_u64 v[30:31], s[0:1], 0, v[184:185]
	s_addc_u32 s23, s63, s23
	v_lshlrev_b32_e32 v13, 6, v34
	s_add_i32 s0, s2, 0x4100
	v_ashrrev_i32_e32 v9, 31, v8
	v_ashrrev_i32_e32 v15, 31, v14
	v_ashrrev_i32_e32 v21, 31, v20
	v_lshlrev_b64 v[22:23], 12, v[18:19]
	v_ashrrev_i32_e32 v27, 31, v26
	v_lshlrev_b64 v[28:29], 12, v[24:25]
	v_lshl_add_u64 v[32:33], s[26:27], 0, v[184:185]
	s_movk_i32 s33, 0x3fff
	v_add_u32_e32 v19, s0, v13
	v_lshlrev_b32_e32 v25, 5, v34
	v_mul_lo_u32 v42, v34, 48
	v_readlane_b32 s5, v253, 33
	v_readlane_b32 s6, v253, 34
	v_readlane_b32 s7, v253, 35
	v_readlane_b32 s8, v253, 36
	v_readlane_b32 s9, v253, 37
	v_readlane_b32 s10, v253, 38
	v_readlane_b32 s11, v253, 39
	v_readlane_b32 s12, v253, 40
	v_readlane_b32 s13, v253, 41
	v_readlane_b32 s14, v253, 42
	v_readlane_b32 s15, v253, 43
	v_readlane_b32 s16, v253, 44
	v_readlane_b32 s17, v253, 45
	s_branch .LBB0_153
